# fox2 row sums as packed add trees, self-max canonicalisations removed
# baseline (speedup 1.0000x reference)
; __device__ __forceinline__ float ex2(float x) { return __builtin_amdgcn_exp2f(x); }
; __device__ __forceinline__ v16f mfma32(v8s a, v8s b, v16f c) { return __builtin_amdgcn_mfma_f32_32x32x16_bf16(a, b, c, 0, 0, 0); }
;     __device__ __forceinline__ bool rowok(int t) const { return ((t < 32 ? (mlo >> t) : (mhi >> (t - 32))) & 1u) != 0u; }
;     __device__ __forceinline__ bool rowok(int t, int sub) const { const unsigned lo = sub ? mloB : mloA, hh = sub ? mhiB : mhiA; return ((t < 32 ? (lo >> t) : (hh >> (t - 32))) & 1u) != 0u; }
; __device__ __forceinline__ void pv_mma(const v4s (&vf)[16], const v16f& p0, const v16f& p1, v16f (&oT)[2]) {
;     v4u w[4];
;     w[0] = (v4u){pkbf(p0[0], p0[1]), pkbf(p0[2], p0[3]), pkbf(p0[4], p0[5]), pkbf(p0[6], p0[7])};
;     w[1] = (v4u){pkbf(p0[8], p0[9]), pkbf(p0[10], p0[11]), pkbf(p0[12], p0[13]), pkbf(p0[14], p0[15])};
;     w[2] = (v4u){pkbf(p1[0], p1[1]), pkbf(p1[2], p1[3]), pkbf(p1[4], p1[5]), pkbf(p1[6], p1[7])};
;     w[3] = (v4u){pkbf(p1[8], p1[9]), pkbf(p1[10], p1[11]), pkbf(p1[12], p1[13]), pkbf(p1[14], p1[15])};
; #pragma unroll
;     for (int ks = 0; ks < 4; ++ks)
; #pragma unroll
;         for (int dt = 0; dt < 2; ++dt) {
;             const v4s lo = vf[4 * ks + 2 * dt], h4 = vf[4 * ks + 2 * dt + 1];
;             const v8s af = (v8s){lo[0], lo[1], lo[2], lo[3], h4[0], h4[1], h4[2], h4[3]};
;             oT[dt] = mfma32(af, __builtin_bit_cast(v8s, w[ks]), oT[dt]);
;         }
; __device__ __forceinline__ void softmax_step(v16f& p0, v16f& p1, v16f (&oT)[2], float& m, float& l, bool rowok) {
;     ...
;     const float mu = (mn == -INFINITY) ? 0.f : mn;
;     const float mue = rowok ? mu : INFINITY;
;     p0 = p0 - mue; p1 = p1 - mue;
; #pragma unroll
;     for (int r = 0; r < 16; ++r) { p0[r] = ex2(p0[r]); p1[r] = ex2(p1[r]); }
;     const v16f s = p0 + p1;
;     l += ((s[0] + s[1]) + (s[2] + s[3])) + ((s[4] + s[5]) + (s[6] + s[7])) + (((s[8] + s[9]) + (s[10] + s[11])) + ((s[12] + s[13]) + (s[14] + s[15])));
.LBB0_215:
	v_cmp_neq_f32_e32 vcc, s76, v253
	s_mul_i32 s60, s73, 0x2080
	v_add_u32_e32 v188, s60, v250
	v_cndmask_b32_e32 v82, 0, v253, vcc
	v_sub_f32_e32 v83, v113, v82
	v_sub_f32_e32 v85, v112, v82
	v_sub_f32_e32 v87, v111, v82
	v_sub_f32_e32 v86, v110, v82
	v_sub_f32_e32 v88, v109, v82
	v_sub_f32_e32 v84, v108, v82
	v_sub_f32_e32 v89, v107, v82
	v_sub_f32_e32 v106, v106, v82
	v_sub_f32_e32 v105, v105, v82
	v_sub_f32_e32 v104, v104, v82
	v_sub_f32_e32 v103, v103, v82
	v_sub_f32_e32 v102, v102, v82
	v_sub_f32_e32 v101, v101, v82
	v_sub_f32_e32 v100, v100, v82
	v_sub_f32_e32 v99, v99, v82
	v_sub_f32_e32 v98, v98, v82
	v_sub_f32_e32 v129, v129, v82
	v_sub_f32_e32 v113, v128, v82
	v_sub_f32_e32 v127, v127, v82
	v_sub_f32_e32 v111, v126, v82
	v_sub_f32_e32 v125, v125, v82
	v_sub_f32_e32 v109, v124, v82
	v_sub_f32_e32 v123, v123, v82
	v_sub_f32_e32 v107, v122, v82
	v_sub_f32_e32 v108, v121, v82
	v_sub_f32_e32 v110, v120, v82
	v_sub_f32_e32 v112, v119, v82
	v_sub_f32_e32 v119, v118, v82
	v_sub_f32_e32 v118, v117, v82
	v_sub_f32_e32 v117, v116, v82
	v_sub_f32_e32 v116, v115, v82
	v_sub_f32_e32 v82, v114, v82
	v_exp_f32_e32 v114, v98
	v_exp_f32_e32 v98, v82
	v_exp_f32_e32 v115, v99
	v_exp_f32_e32 v99, v116
	v_exp_f32_e32 v116, v100
	v_exp_f32_e32 v100, v117
	v_exp_f32_e32 v117, v101
	v_exp_f32_e32 v101, v118
	v_exp_f32_e32 v118, v102
	v_exp_f32_e32 v102, v119
	v_exp_f32_e32 v119, v103
	v_exp_f32_e32 v103, v112
	v_exp_f32_e32 v120, v104
	v_exp_f32_e32 v104, v110
	v_exp_f32_e32 v121, v105
	v_exp_f32_e32 v105, v108
	v_exp_f32_e32 v106, v106
	v_exp_f32_e32 v82, v107
	v_exp_f32_e32 v107, v89
	v_exp_f32_e32 v108, v84
	v_exp_f32_e32 v84, v109
	v_exp_f32_e32 v109, v88
	v_exp_f32_e32 v110, v86
	v_exp_f32_e32 v86, v111
	v_exp_f32_e32 v111, v87
	v_exp_f32_e32 v112, v85
	v_exp_f32_e32 v88, v113
	v_exp_f32_e32 v113, v83
	v_exp_f32_e32 v89, v129
	v_exp_f32_e32 v87, v127
	v_exp_f32_e32 v85, v125
	v_exp_f32_e32 v83, v123
	v_pk_add_f32 v[122:123], v[112:113], v[88:89]
	v_pk_add_f32 v[124:125], v[110:111], v[86:87]
	v_pk_add_f32 v[126:127], v[108:109], v[84:85]
	v_pk_add_f32 v[128:129], v[106:107], v[82:83]
	v_pk_add_f32 v[170:171], v[120:121], v[104:105]
	v_pk_add_f32 v[174:175], v[118:119], v[102:103]
	v_pk_add_f32 v[178:179], v[116:117], v[100:101]
	v_pk_add_f32 v[182:183], v[114:115], v[98:99]
	v_pk_add_f32 v[122:123], v[122:123], v[124:125]
	v_pk_add_f32 v[126:127], v[126:127], v[128:129]
	v_pk_add_f32 v[170:171], v[170:171], v[174:175]
	v_pk_add_f32 v[178:179], v[178:179], v[182:183]
	v_pk_add_f32 v[122:123], v[122:123], v[126:127]
	v_pk_add_f32 v[170:171], v[170:171], v[178:179]
	v_cmp_neq_f32_e32 vcc, s76, v237
	v_pk_add_f32 v[122:123], v[122:123], v[170:171]
	v_cvt_pk_bf16_f32 v106, v106, v107
	v_add_f32_e32 v122, v122, v123
	v_add_f32_e32 v252, v252, v122
	v_cndmask_b32_e32 v122, 0, v237, vcc
	v_sub_f32_e32 v129, v81, v122
	v_sub_f32_e32 v170, v80, v122
	v_sub_f32_e32 v127, v79, v122
	v_sub_f32_e32 v126, v78, v122
	v_sub_f32_e32 v123, v77, v122
	v_sub_f32_e32 v124, v76, v122
	v_sub_f32_e32 v125, v75, v122
	v_sub_f32_e32 v128, v74, v122
	v_sub_f32_e32 v175, v185, v122
	v_sub_f32_e32 v178, v184, v122
	v_sub_f32_e32 v183, v93, v122
	v_sub_f32_e32 v184, v92, v122
	v_sub_f32_e32 v185, v91, v122
	v_sub_f32_e32 v186, v90, v122
	ds_read_b64_tr_b16 v[74:75], v188 offset:27648
	ds_read_b64_tr_b16 v[76:77], v188 offset:28160
	ds_read_b64_tr_b16 v[78:79], v188 offset:31808
	ds_read_b64_tr_b16 v[80:81], v188 offset:32320
	ds_read_b64_tr_b16 v[90:91], v188 offset:34880
	ds_read_b64_tr_b16 v[92:93], v188 offset:35392
	v_sub_f32_e32 v171, v173, v122
	v_sub_f32_e32 v173, v181, v122
	v_sub_f32_e32 v174, v180, v122
	v_sub_f32_e32 v179, v97, v122
	v_sub_f32_e32 v180, v96, v122
	v_sub_f32_e32 v181, v95, v122
	v_sub_f32_e32 v182, v94, v122
	v_cvt_pk_bf16_f32 v94, v114, v115
	v_cvt_pk_bf16_f32 v95, v116, v117
	v_cvt_pk_bf16_f32 v96, v118, v119
	v_cvt_pk_bf16_f32 v97, v120, v121
	v_sub_f32_e32 v187, v71, v122
	v_sub_f32_e32 v189, v70, v122
	s_waitcnt lgkmcnt(4)
; __device__ __forceinline__ float ex2(float x) { return __builtin_amdgcn_exp2f(x); }
; __device__ __forceinline__ v16f mfma32(v8s a, v8s b, v16f c) { return __builtin_amdgcn_mfma_f32_32x32x16_bf16(a, b, c, 0, 0, 0); }
;     __device__ __forceinline__ bool rowok(int t) const { return ((t < 32 ? (mlo >> t) : (mhi >> (t - 32))) & 1u) != 0u; }
;     __device__ __forceinline__ bool rowok(int t, int sub) const { const unsigned lo = sub ? mloB : mloA, hh = sub ? mhiB : mhiA; return ((t < 32 ? (lo >> t) : (hh >> (t - 32))) & 1u) != 0u; }
; __device__ __forceinline__ void pv_mma(const v4s (&vf)[16], const v16f& p0, const v16f& p1, v16f (&oT)[2]) {
;     v4u w[4];
;     w[0] = (v4u){pkbf(p0[0], p0[1]), pkbf(p0[2], p0[3]), pkbf(p0[4], p0[5]), pkbf(p0[6], p0[7])};
;     w[1] = (v4u){pkbf(p0[8], p0[9]), pkbf(p0[10], p0[11]), pkbf(p0[12], p0[13]), pkbf(p0[14], p0[15])};
;     w[2] = (v4u){pkbf(p1[0], p1[1]), pkbf(p1[2], p1[3]), pkbf(p1[4], p1[5]), pkbf(p1[6], p1[7])};
;     w[3] = (v4u){pkbf(p1[8], p1[9]), pkbf(p1[10], p1[11]), pkbf(p1[12], p1[13]), pkbf(p1[14], p1[15])};
; #pragma unroll
;     for (int ks = 0; ks < 4; ++ks)
; #pragma unroll
;         for (int dt = 0; dt < 2; ++dt) {
;             const v4s lo = vf[4 * ks + 2 * dt], h4 = vf[4 * ks + 2 * dt + 1];
;             const v8s af = (v8s){lo[0], lo[1], lo[2], lo[3], h4[0], h4[1], h4[2], h4[3]};
;             oT[dt] = mfma32(af, __builtin_bit_cast(v8s, w[ks]), oT[dt]);
;         }
; __device__ __forceinline__ void softmax_step(v16f& p0, v16f& p1, v16f (&oT)[2], float& m, float& l, bool rowok) {
;     ...
;     const float mu = (mn == -INFINITY) ? 0.f : mn;
;     const float mue = rowok ? mu : INFINITY;
;     p0 = p0 - mue; p1 = p1 - mue;
; #pragma unroll
;     for (int r = 0; r < 16; ++r) { p0[r] = ex2(p0[r]); p1[r] = ex2(p1[r]); }
;     const v16f s = p0 + p1;
;     l += ((s[0] + s[1]) + (s[2] + s[3])) + ((s[4] + s[5]) + (s[6] + s[7])) + (((s[8] + s[9]) + (s[10] + s[11])) + ((s[12] + s[13]) + (s[14] + s[15])));
	v_mfma_f32_32x32x16_bf16 v[50:65], v[74:77], v[94:97], v[50:65]
	v_sub_f32_e32 v190, v73, v122
	v_sub_f32_e32 v191, v72, v122
	ds_read_b64_tr_b16 v[70:71], v188 offset:28672
	ds_read_b64_tr_b16 v[72:73], v188 offset:29184
	ds_read_b64_tr_b16 v[114:115], v188 offset:30720
	ds_read_b64_tr_b16 v[116:117], v188 offset:31232
	v_cvt_pk_bf16_f32 v107, v108, v109
	v_cvt_pk_bf16_f32 v108, v110, v111
	v_cvt_pk_bf16_f32 v109, v112, v113
	v_sub_f32_e32 v112, v67, v122
	s_waitcnt lgkmcnt(6)
	v_mfma_f32_32x32x16_bf16 v[34:49], v[78:81], v[94:97], v[34:49]
	ds_read_b64_tr_b16 v[94:95], v188 offset:32832
	ds_read_b64_tr_b16 v[96:97], v188 offset:33344
	ds_read_b64_tr_b16 v[118:119], v188 offset:29696
	ds_read_b64_tr_b16 v[120:121], v188 offset:30208
	v_sub_f32_e32 v113, v66, v122
	v_sub_f32_e32 v192, v69, v122
	v_sub_f32_e32 v111, v68, v122
	ds_read_b64_tr_b16 v[66:67], v188 offset:33856
	ds_read_b64_tr_b16 v[68:69], v188 offset:34368
	v_cvt_pk_bf16_f32 v98, v98, v99
	v_cvt_pk_bf16_f32 v99, v100, v101
	s_waitcnt lgkmcnt(8)
	v_mfma_f32_32x32x16_bf16 v[50:65], v[70:73], v[106:109], v[50:65]
	v_cvt_pk_bf16_f32 v100, v102, v103
	v_cvt_pk_bf16_f32 v101, v104, v105
	v_sub_f32_e32 v172, v172, v122
	v_sub_f32_e32 v177, v177, v122
	v_sub_f32_e32 v176, v176, v122
	v_exp_f32_e32 v110, v176
	v_exp_f32_e32 v102, v178
	s_waitcnt lgkmcnt(4)
	v_mfma_f32_32x32x16_bf16 v[34:49], v[94:97], v[106:109], v[34:49]
	v_exp_f32_e32 v106, v111
	v_exp_f32_e32 v111, v177
	v_exp_f32_e32 v103, v175
	v_exp_f32_e32 v108, v174
	v_exp_f32_e32 v109, v173
	v_cvt_pk_bf16_f32 v82, v82, v83
	v_cvt_pk_bf16_f32 v83, v84, v85
	s_waitcnt lgkmcnt(2)
	v_mfma_f32_32x32x16_bf16 v[50:65], v[118:121], v[98:101], v[50:65]
	v_cvt_pk_bf16_f32 v84, v86, v87
	v_cvt_pk_bf16_f32 v85, v88, v89
	v_exp_f32_e32 v86, v128
	v_exp_f32_e32 v87, v125
	v_exp_f32_e32 v122, v124
	v_exp_f32_e32 v123, v123
	v_exp_f32_e32 v126, v126
	s_waitcnt lgkmcnt(0)
	v_mfma_f32_32x32x16_bf16 v[34:49], v[66:69], v[98:101], v[34:49]
	v_exp_f32_e32 v98, v172
	v_exp_f32_e32 v99, v171
	v_exp_f32_e32 v127, v127
	v_exp_f32_e32 v170, v170
	v_exp_f32_e32 v171, v129
	v_exp_f32_e32 v107, v192
	v_exp_f32_e32 v88, v186
	v_mfma_f32_32x32x16_bf16 v[50:65], v[114:117], v[82:85], v[50:65]
	v_exp_f32_e32 v89, v185
	v_exp_f32_e32 v104, v113
	v_exp_f32_e32 v105, v112
	v_exp_f32_e32 v112, v191
	v_exp_f32_e32 v113, v190
	v_exp_f32_e32 v100, v189
	v_exp_f32_e32 v101, v187
	v_mfma_f32_32x32x16_bf16 v[34:49], v[90:93], v[82:85], v[34:49]
	v_cvt_pk_bf16_f32 v82, v110, v111
	v_cvt_pk_bf16_f32 v83, v102, v103
	v_cvt_pk_bf16_f32 v84, v108, v109
	v_cvt_pk_bf16_f32 v85, v98, v99
	v_exp_f32_e32 v124, v184
	v_exp_f32_e32 v125, v183
	v_exp_f32_e32 v128, v182
	v_mfma_f32_32x32x16_bf16 v[18:33], v[74:77], v[82:85], v[18:33]
	v_cvt_pk_bf16_f32 v74, v86, v87
	v_cvt_pk_bf16_f32 v75, v122, v123
	v_cvt_pk_bf16_f32 v76, v126, v127
	v_cvt_pk_bf16_f32 v77, v170, v171
	v_exp_f32_e32 v172, v180
	v_exp_f32_e32 v173, v179
	v_exp_f32_e32 v129, v181
	v_mfma_f32_32x32x16_bf16 v[2:17], v[78:81], v[82:85], v[2:17]
	v_pk_add_f32 v[174:175], v[110:111], v[102:103]
	v_pk_add_f32 v[176:177], v[108:109], v[98:99]
	v_pk_add_f32 v[178:179], v[86:87], v[122:123]
	v_pk_add_f32 v[180:181], v[126:127], v[170:171]
	v_pk_add_f32 v[182:183], v[106:107], v[104:105]
	v_pk_add_f32 v[184:185], v[112:113], v[100:101]
	v_mfma_f32_32x32x16_bf16 v[18:33], v[70:73], v[74:77], v[18:33]
	v_cvt_pk_bf16_f32 v70, v106, v107
	v_cvt_pk_bf16_f32 v71, v104, v105
	v_pk_add_f32 v[186:187], v[88:89], v[124:125]
	v_pk_add_f32 v[188:189], v[128:129], v[172:173]
	v_pk_add_f32 v[174:175], v[174:175], v[176:177]
	v_pk_add_f32 v[178:179], v[178:179], v[180:181]
	v_mfma_f32_32x32x16_bf16 v[2:17], v[94:97], v[74:77], v[2:17]
	v_cvt_pk_bf16_f32 v72, v112, v113
	v_cvt_pk_bf16_f32 v73, v100, v101
	v_pk_add_f32 v[182:183], v[182:183], v[184:185]
	v_pk_add_f32 v[186:187], v[186:187], v[188:189]
	v_mfma_f32_32x32x16_bf16 v[18:33], v[118:121], v[70:73], v[18:33]
	v_pk_add_f32 v[174:175], v[174:175], v[178:179]
	v_pk_add_f32 v[182:183], v[182:183], v[186:187]
	v_mfma_f32_32x32x16_bf16 v[2:17], v[66:69], v[70:73], v[2:17]
	v_pk_add_f32 v[174:175], v[174:175], v[182:183]
	v_cvt_pk_bf16_f32 v66, v88, v89
	v_cvt_pk_bf16_f32 v67, v124, v125
	v_cvt_pk_bf16_f32 v68, v128, v129
	v_cvt_pk_bf16_f32 v69, v172, v173
	v_add_f32_e32 v174, v174, v175
	v_add_f32_e32 v251, v251, v174
	v_mfma_f32_32x32x16_bf16 v[18:33], v[114:117], v[66:69], v[18:33]
	v_mfma_f32_32x32x16_bf16 v[2:17], v[90:93], v[66:69], v[2:17]

; __device__ __forceinline__ float ex2(float x) { return __builtin_amdgcn_exp2f(x); }
; __device__ __forceinline__ float max3f(float a, float b, float c) { return __builtin_fmaxf(__builtin_fmaxf(a, b), c); }
;     __device__ __forceinline__ bool rowok(int t) const { return ((t < 32 ? (mlo >> t) : (mhi >> (t - 32))) & 1u) != 0u; }
;     __device__ __forceinline__ bool rowok(int t, int sub) const { const unsigned lo = sub ? mloB : mloA, hh = sub ? mhiB : mhiA; return ((t < 32 ? (lo >> t) : (hh >> (t - 32))) & 1u) != 0u; }
; __device__ __forceinline__ void softmax_step(v16f& p0, v16f& p1, v16f (&oT)[2], float& m, float& l, bool rowok) {
;     float a = max3f(p0[0], p0[1], p1[0]), b = max3f(p0[2], p0[3], p1[1]); a = max3f(a, p1[2], p1[3]);
; #pragma unroll
;     for (int r = 4; r < 16; r += 4) { a = max3f(a, p0[r], p0[r + 1]); b = max3f(b, p0[r + 2], p0[r + 3]); a = max3f(a, p1[r], p1[r + 1]); b = max3f(b, p1[r + 2], p1[r + 3]); }
;     float mx = fmaxf(a, b);
;     mx = xhalf_max(mx);
;     if (!rowok) mx = -INFINITY;
;     float mn = m;
;     if (__any(mx > m + SM_THR)) {
;         mn = fmaxf(m, mx);
;         const float mu_ = (mn == -INFINITY) ? 0.f : mn;
;         const float alpha = ex2(m - mu_);
;         oT[0] = oT[0] * alpha; oT[1] = oT[1] * alpha; l *= alpha;
;     }
.LBB0_233:
	v_max_f32_e32 v82, v98, v99
	v_max3_f32 v83, v100, v101, v115
	v_max3_f32 v82, v82, v114, v116
	v_max3_f32 v82, v82, v117, v102
	v_max3_f32 v83, v83, v104, v105
	v_max3_f32 v82, v82, v103, v118
	v_max3_f32 v83, v83, v120, v121
	v_max3_f32 v82, v82, v119, v106
	v_max3_f32 v83, v83, v108, v109
	v_max3_f32 v82, v82, v107, v122
	v_max3_f32 v83, v83, v124, v125
	v_max3_f32 v82, v82, v123, v110
	v_max3_f32 v83, v83, v112, v113
	v_max3_f32 v82, v82, v111, v126
	v_max3_f32 v83, v83, v128, v129
	v_max3_f32 v82, v82, v127, v83
	v_mov_b32_e32 v83, v82
	s_nop 1
	v_permlane32_swap_b32_e32 v82, v83
	v_max_f32_e32 v82, v82, v83
	v_add_f32_e32 v83, 0x41800000, v253
	v_cmp_gt_f32_e32 vcc, v82, v83
	s_mov_b32 s76, 0xff800000
	s_cbranch_vccz .LBB0_235
	v_max_f32_e32 v82, v82, v82
	v_max_f32_e32 v83, v253, v253
	v_max_f32_e32 v83, v83, v82
	v_cmp_neq_f32_e32 vcc, s76, v83
	s_nop 1
	v_cndmask_b32_e32 v82, 0, v83, vcc
	v_sub_f32_e32 v82, v253, v82
	v_exp_f32_e32 v82, v82
	v_mov_b32_e32 v253, v83
	v_pk_mul_f32 v[64:65], v[64:65], v[82:83] op_sel_hi:[1,0]
	v_pk_mul_f32 v[62:63], v[62:63], v[82:83] op_sel_hi:[1,0]
	v_pk_mul_f32 v[60:61], v[60:61], v[82:83] op_sel_hi:[1,0]
	v_pk_mul_f32 v[58:59], v[58:59], v[82:83] op_sel_hi:[1,0]
	v_pk_mul_f32 v[56:57], v[56:57], v[82:83] op_sel_hi:[1,0]
	v_pk_mul_f32 v[54:55], v[54:55], v[82:83] op_sel_hi:[1,0]
	v_pk_mul_f32 v[52:53], v[52:53], v[82:83] op_sel_hi:[1,0]
	v_pk_mul_f32 v[50:51], v[50:51], v[82:83] op_sel_hi:[1,0]
	v_pk_mul_f32 v[48:49], v[48:49], v[82:83] op_sel_hi:[1,0]
	v_pk_mul_f32 v[46:47], v[46:47], v[82:83] op_sel_hi:[1,0]
	v_pk_mul_f32 v[44:45], v[44:45], v[82:83] op_sel_hi:[1,0]
	v_pk_mul_f32 v[42:43], v[42:43], v[82:83] op_sel_hi:[1,0]
	v_pk_mul_f32 v[40:41], v[40:41], v[82:83] op_sel_hi:[1,0]
	v_pk_mul_f32 v[38:39], v[38:39], v[82:83] op_sel_hi:[1,0]
	v_pk_mul_f32 v[36:37], v[36:37], v[82:83] op_sel_hi:[1,0]
	v_pk_mul_f32 v[34:35], v[34:35], v[82:83] op_sel_hi:[1,0]
	v_mul_f32_e32 v252, v252, v82
.LBB0_235:
	v_max_f32_e32 v82, v176, v177
	v_max3_f32 v83, v184, v185, v69
	v_max3_f32 v82, v82, v68, v66
	v_max3_f32 v82, v82, v67, v180
	v_max3_f32 v83, v83, v172, v173
	v_max3_f32 v82, v82, v181, v72
	v_max3_f32 v83, v83, v70, v71
	v_max3_f32 v82, v82, v73, v74
	v_max3_f32 v83, v83, v76, v77
	v_max3_f32 v82, v82, v75, v90
	v_max3_f32 v83, v83, v92, v93
	v_max3_f32 v82, v82, v91, v78
	v_max3_f32 v83, v83, v80, v81
	v_max3_f32 v82, v82, v79, v94
	v_max3_f32 v83, v83, v96, v97
	v_max3_f32 v82, v82, v95, v83
	v_mov_b32_e32 v83, v82
	s_nop 1
	v_permlane32_swap_b32_e32 v82, v83
	v_max_f32_e32 v82, v82, v83
	v_add_f32_e32 v83, 0x41800000, v237
	v_cmp_gt_f32_e32 vcc, v82, v83
	s_cbranch_vccz .LBB0_215
	v_max_f32_e32 v82, v82, v82
	v_max_f32_e32 v83, v237, v237
	v_max_f32_e32 v83, v83, v82
	v_cmp_neq_f32_e32 vcc, s76, v83
	s_nop 1
	v_cndmask_b32_e32 v82, 0, v83, vcc
	v_sub_f32_e32 v82, v237, v82
	v_exp_f32_e32 v82, v82
	v_mov_b32_e32 v237, v83
	v_pk_mul_f32 v[32:33], v[32:33], v[82:83] op_sel_hi:[1,0]
	v_pk_mul_f32 v[30:31], v[30:31], v[82:83] op_sel_hi:[1,0]
	v_pk_mul_f32 v[28:29], v[28:29], v[82:83] op_sel_hi:[1,0]
	v_pk_mul_f32 v[26:27], v[26:27], v[82:83] op_sel_hi:[1,0]
	v_pk_mul_f32 v[24:25], v[24:25], v[82:83] op_sel_hi:[1,0]
	v_pk_mul_f32 v[22:23], v[22:23], v[82:83] op_sel_hi:[1,0]
	v_pk_mul_f32 v[20:21], v[20:21], v[82:83] op_sel_hi:[1,0]
	v_pk_mul_f32 v[18:19], v[18:19], v[82:83] op_sel_hi:[1,0]
	v_pk_mul_f32 v[16:17], v[16:17], v[82:83] op_sel_hi:[1,0]
	v_pk_mul_f32 v[14:15], v[14:15], v[82:83] op_sel_hi:[1,0]
	v_pk_mul_f32 v[12:13], v[12:13], v[82:83] op_sel_hi:[1,0]
	v_pk_mul_f32 v[10:11], v[10:11], v[82:83] op_sel_hi:[1,0]
	v_pk_mul_f32 v[8:9], v[8:9], v[82:83] op_sel_hi:[1,0]
	v_pk_mul_f32 v[6:7], v[6:7], v[82:83] op_sel_hi:[1,0]
	v_pk_mul_f32 v[4:5], v[4:5], v[82:83] op_sel_hi:[1,0]
	v_pk_mul_f32 v[2:3], v[2:3], v[82:83] op_sel_hi:[1,0]
	v_mul_f32_e32 v251, v251, v82
	s_branch .LBB0_215
